# v5 + select pass rewritten (4 independent VALU counters, straight-line groups) + work-queue ticket prefetch
# baseline (speedup 1.0000x reference)
.LBB0_1116:
	v_writelane_b32 v251, s94, 50
	s_add_u32 s0, s90, 0x232a0800
	s_mul_i32 s7, s38, 0x82000
	v_writelane_b32 v251, s95, 51
	v_writelane_b32 v251, s0, 52
	s_addc_u32 s0, s91, 0
	v_writelane_b32 v251, s0, 54
	s_ashr_i32 s0, s38, 31
	v_writelane_b32 v251, s0, 56
	s_mul_hi_i32 s6, s38, 0x82000
	s_add_u32 s0, s90, s7
	s_addc_u32 s1, s91, s6
	s_add_u32 s4, s0, 0x23ab6800
	s_addc_u32 s5, s1, 0
	s_add_u32 s0, s90, 0x23ab67f8
	s_addc_u32 s1, s91, 0
	v_writelane_b32 v251, s0, 48
	s_waitcnt vmcnt(1)
	v_lshrrev_b32_e32 v1, 5, v192
	v_mov_b32_e32 v197, 0
	v_writelane_b32 v251, s1, 49
	s_add_u32 s0, s90, 0x22aa0800
	v_writelane_b32 v251, s0, 57
	s_addc_u32 s0, s91, 0
	v_lshlrev_b32_e32 v196, 4, v1
	v_writelane_b32 v251, s0, 59
	v_lshl_add_u64 v[2:3], s[90:91], 0, v[196:197]
	s_mov_b64 s[0:1], 0x20a80800
	s_add_u32 s62, s90, 0x236b0800
	v_and_b32_e32 v194, 31, v96
	v_lshl_add_u64 v[198:199], v[2:3], 0, s[0:1]
	s_addc_u32 s63, s91, 0
	s_lshl_b32 s0, s92, 5
	v_or_b32_e32 v2, s0, v194
	v_ashrrev_i32_e32 v3, 31, v2
	v_lshlrev_b32_e32 v200, 2, v1
	s_mov_b32 s65, s0
	v_lshlrev_b64 v[208:209], 7, v[2:3]
	s_movk_i32 s0, 0x4100
	v_mov_b64_e32 v[2:3], s[4:5]
	v_mad_u64_u32 v[2:3], s[0:1], v200, s0, v[2:3]
	s_cmp_lt_i32 s92, 32
	s_cselect_b64 s[0:1], -1, 0
	v_writelane_b32 v251, s0, 46
	s_mul_i32 s9, s92, 0x4100
	v_lshlrev_b32_e32 v196, 2, v194
	v_writelane_b32 v251, s1, 47
	s_mul_hi_i32 s8, s92, 0x4100
	s_add_u32 s0, s4, s9
	v_lshl_add_u64 v[210:211], v[2:3], 0, v[196:197]
	s_addc_u32 s1, s5, s8
	v_lshlrev_b32_e32 v196, 2, v192
	v_lshl_add_u64 v[212:213], s[0:1], 0, v[196:197]
	s_lshl_b32 s0, s92, 10
	s_add_u32 s94, s90, 0x33eb6800
	v_writelane_b32 v251, s4, 61
	s_addc_u32 s95, s91, 0
	s_add_i32 s93, s0, 0
	v_writelane_b32 v251, s5, 62
	s_add_u32 s0, s90, 0x20260800
	v_writelane_b32 v251, s0, 63
	s_addc_u32 s0, s91, 0
	v_lshlrev_b64 v[2:3], v192, -1
	v_writelane_b32 v250, s0, 0
	s_add_u32 s0, s90, 0x1fa40800
	v_writelane_b32 v250, s0, 1
	s_addc_u32 s0, s91, 0
	v_writelane_b32 v250, s0, 2
	s_add_u32 s0, s90, 0x17980800
	v_writelane_b32 v250, s0, 3
	s_addc_u32 s0, s91, 0
	v_writelane_b32 v250, s0, 4
	s_add_u32 s0, s90, 0x15900800
	v_writelane_b32 v250, s0, 5
	s_addc_u32 s0, s91, 0
	v_writelane_b32 v250, s0, 6
	s_add_u32 s0, s7, s9
	s_addc_u32 s1, s6, s8
	s_add_u32 s0, s90, s0
	s_addc_u32 s1, s91, s1
	s_add_u32 s0, s0, 0x23ab6800
	v_ashrrev_i32_e32 v97, 31, v96
	v_writelane_b32 v250, s0, 7
	s_addc_u32 s0, s1, 0
	v_lshlrev_b32_e32 v0, 3, v1
	v_not_b32_e32 v217, v3
	v_not_b32_e32 v216, v2
	v_writelane_b32 v250, s0, 9
	v_lshlrev_b64 v[2:3], 5, v[96:97]
	s_mov_b64 s[0:1], 0xc010
	s_mov_b32 s61, 0
	v_cmp_eq_u32_e64 s[2:3], 0, v96
	v_or_b32_e32 v229, 0x1000, v192
	v_mov_b32_e32 v195, v197
	v_or_b32_e32 v202, 24, v200
	v_mov_b32_e32 v203, v197
	v_or_b32_e32 v204, 16, v200
	v_mov_b32_e32 v205, v197
	v_or_b32_e32 v206, 8, v200
	v_mov_b32_e32 v207, v197
	v_mov_b32_e32 v201, v197
	v_mov_b32_e32 v193, v197
	v_lshl_add_u64 v[214:215], s[4:5], 0, v[196:197]
	v_cmp_eq_u32_e64 s[4:5], 0, v192
	v_lshlrev_b32_e32 v230, 6, v192
	v_lshl_add_u32 v231, v192, 3, s93
	v_lshlrev_b64 v[218:219], 3, v[96:97]
	v_xor_b32_e32 v232, 0x1e0, v192
	v_or_b32_e32 v221, 64, v192
	v_mov_b32_e32 v220, v192
	v_or_b32_e32 v233, 0x100, v194
	v_lshl_add_u64 v[222:223], v[2:3], 0, s[0:1]
	v_lshlrev_b32_e32 v224, 1, v0
	s_movk_i32 s0, 0x4000
	v_mov_b32_e32 v234, 0xff800000
	v_mov_b32_e32 v235, 0x4100
	v_lshrrev_b32_e32 v252, 5, v192
	v_and_b32_e32 v253, 31, v192
	v_mul_u32_u24_e32 v252, 0x240, v252
	v_lshl_add_u32 v252, v253, 2, v252
	s_mul_i32 s100, s92, 0x1200
	s_add_i32 s100, s100, 0x10000
	v_add_u32_e32 v252, s100, v252
	v_lshrrev_b32_e32 v253, 3, v192
	v_and_b32_e32 v254, 7, v192
	v_mul_u32_u24_e32 v255, 0x90, v253
	v_lshl_add_u32 v255, v254, 4, v255
	v_mul_u32_u24_e32 v253, 0x4100, v253
	v_lshl_add_u32 v254, v254, 4, v253
	v_add_u32_e32 v253, s100, v255
	v_readlane_b32 s98, v251, 61
	v_readlane_b32 s99, v251, 62
	s_and_saveexec_b64 s[6:7], s[2:3]
	s_cbranch_execz .Lq2_pre
	v_readlane_b32 s10, v251, 48
	v_readlane_b32 s11, v251, 49
	v_mov_b32_e32 v1, 1
	s_nop 3
	global_atomic_add v255, v197, v1, s[10:11] sc0
.Lq2_pre:
	s_or_b64 exec, exec, s[6:7]
	s_branch .LBB0_1119

.LBB0_1119:
	s_and_saveexec_b64 s[6:7], s[2:3]
	s_cbranch_execz .LBB0_1123
	v_readlane_b32 s10, v251, 48
	v_readlane_b32 s11, v251, 49
	s_waitcnt vmcnt(0)
	ds_write_b32 v197, v255 offset:60000
	v_mov_b32_e32 v1, 1
	s_nop 1
	global_atomic_add v255, v197, v1, s[10:11] sc0

.LBB0_1244:
	v_cmp_le_u32_e64 s[28:29], s35, v58
	v_cmp_le_u32_e64 s[38:39], s35, v59
	v_cmp_le_u32_e64 s[40:41], s35, v126
	v_cmp_le_u32_e64 s[42:43], s35, v127
	v_cmp_le_u32_e64 s[44:45], s35, v128
	v_cmp_le_u32_e64 s[46:47], s35, v129
	v_cmp_le_u32_e64 s[48:49], s35, v130
	v_cmp_le_u32_e64 s[50:51], s35, v131
	v_cndmask_b32_e64 v160, 0, 1, s[28:29]
	v_cndmask_b32_e64 v161, 0, 1, s[38:39]
	v_cndmask_b32_e64 v162, 0, 1, s[40:41]
	v_cndmask_b32_e64 v163, 0, 1, s[42:43]
	v_addc_co_u32_e64 v160, s[44:45], 0, v160, s[44:45]
	v_addc_co_u32_e64 v161, s[46:47], 0, v161, s[46:47]
	v_addc_co_u32_e64 v162, s[48:49], 0, v162, s[48:49]
	v_addc_co_u32_e64 v163, s[50:51], 0, v163, s[50:51]
	s_and_b64 vcc, exec, s[22:23]
	s_cbranch_vccnz .Lsel_red
	v_cmp_le_u32_e64 s[28:29], s35, v84
	v_cmp_le_u32_e64 s[38:39], s35, v79
	v_cmp_le_u32_e64 s[40:41], s35, v98
	v_cmp_le_u32_e64 s[42:43], s35, v93
	v_cmp_le_u32_e64 s[44:45], s35, v113
	v_cmp_le_u32_e64 s[46:47], s35, v107
	v_cmp_le_u32_e64 s[48:49], s35, v123
	v_cmp_le_u32_e64 s[50:51], s35, v118
	v_addc_co_u32_e64 v160, s[28:29], 0, v160, s[28:29]
	v_addc_co_u32_e64 v161, s[38:39], 0, v161, s[38:39]
	v_addc_co_u32_e64 v162, s[40:41], 0, v162, s[40:41]
	v_addc_co_u32_e64 v163, s[42:43], 0, v163, s[42:43]
	v_addc_co_u32_e64 v160, s[44:45], 0, v160, s[44:45]
	v_addc_co_u32_e64 v161, s[46:47], 0, v161, s[46:47]
	v_addc_co_u32_e64 v162, s[48:49], 0, v162, s[48:49]
	v_addc_co_u32_e64 v163, s[50:51], 0, v163, s[50:51]
	s_and_b64 vcc, exec, s[20:21]
	s_cbranch_vccnz .Lsel_red
	v_cmp_le_u32_e64 s[28:29], s35, v82
	v_cmp_le_u32_e64 s[38:39], s35, v75
	v_cmp_le_u32_e64 s[40:41], s35, v96
	v_cmp_le_u32_e64 s[42:43], s35, v89
	v_cmp_le_u32_e64 s[44:45], s35, v110
	v_cmp_le_u32_e64 s[46:47], s35, v103
	v_cmp_le_u32_e64 s[48:49], s35, v121
	v_cmp_le_u32_e64 s[50:51], s35, v62
	v_addc_co_u32_e64 v160, s[28:29], 0, v160, s[28:29]
	v_addc_co_u32_e64 v161, s[38:39], 0, v161, s[38:39]
	v_addc_co_u32_e64 v162, s[40:41], 0, v162, s[40:41]
	v_addc_co_u32_e64 v163, s[42:43], 0, v163, s[42:43]
	v_addc_co_u32_e64 v160, s[44:45], 0, v160, s[44:45]
	v_addc_co_u32_e64 v161, s[46:47], 0, v161, s[46:47]
	v_addc_co_u32_e64 v162, s[48:49], 0, v162, s[48:49]
	v_addc_co_u32_e64 v163, s[50:51], 0, v163, s[50:51]
	s_and_b64 vcc, exec, s[18:19]
	s_cbranch_vccnz .Lsel_red
	v_cmp_le_u32_e64 s[28:29], s35, v83
	v_cmp_le_u32_e64 s[38:39], s35, v76
	v_cmp_le_u32_e64 s[40:41], s35, v97
	v_cmp_le_u32_e64 s[42:43], s35, v90
	v_cmp_le_u32_e64 s[44:45], s35, v111
	v_cmp_le_u32_e64 s[46:47], s35, v104
	v_cmp_le_u32_e64 s[48:49], s35, v122
	v_cmp_le_u32_e64 s[50:51], s35, v115
	v_addc_co_u32_e64 v160, s[28:29], 0, v160, s[28:29]
	v_addc_co_u32_e64 v161, s[38:39], 0, v161, s[38:39]
	v_addc_co_u32_e64 v162, s[40:41], 0, v162, s[40:41]
	v_addc_co_u32_e64 v163, s[42:43], 0, v163, s[42:43]
	v_addc_co_u32_e64 v160, s[44:45], 0, v160, s[44:45]
	v_addc_co_u32_e64 v161, s[46:47], 0, v161, s[46:47]
	v_addc_co_u32_e64 v162, s[48:49], 0, v162, s[48:49]
	v_addc_co_u32_e64 v163, s[50:51], 0, v163, s[50:51]
	s_and_b64 vcc, exec, s[16:17]
	s_cbranch_vccnz .Lsel_red
	v_cmp_le_u32_e64 s[28:29], s35, v80
	v_cmp_le_u32_e64 s[38:39], s35, v73
	v_cmp_le_u32_e64 s[40:41], s35, v94
	v_cmp_le_u32_e64 s[42:43], s35, v87
	v_cmp_le_u32_e64 s[44:45], s35, v108
	v_cmp_le_u32_e64 s[46:47], s35, v101
	v_cmp_le_u32_e64 s[48:49], s35, v119
	v_cmp_le_u32_e64 s[50:51], s35, v61
	v_addc_co_u32_e64 v160, s[28:29], 0, v160, s[28:29]
	v_addc_co_u32_e64 v161, s[38:39], 0, v161, s[38:39]
	v_addc_co_u32_e64 v162, s[40:41], 0, v162, s[40:41]
	v_addc_co_u32_e64 v163, s[42:43], 0, v163, s[42:43]
	v_addc_co_u32_e64 v160, s[44:45], 0, v160, s[44:45]
	v_addc_co_u32_e64 v161, s[46:47], 0, v161, s[46:47]
	v_addc_co_u32_e64 v162, s[48:49], 0, v162, s[48:49]
	v_addc_co_u32_e64 v163, s[50:51], 0, v163, s[50:51]
	s_and_b64 vcc, exec, s[14:15]
	s_cbranch_vccnz .Lsel_red
	v_cmp_le_u32_e64 s[28:29], s35, v81
	v_cmp_le_u32_e64 s[38:39], s35, v74
	v_cmp_le_u32_e64 s[40:41], s35, v95
	v_cmp_le_u32_e64 s[42:43], s35, v88
	v_cmp_le_u32_e64 s[44:45], s35, v109
	v_cmp_le_u32_e64 s[46:47], s35, v102
	v_cmp_le_u32_e64 s[48:49], s35, v120
	v_cmp_le_u32_e64 s[50:51], s35, v114
	v_addc_co_u32_e64 v160, s[28:29], 0, v160, s[28:29]
	v_addc_co_u32_e64 v161, s[38:39], 0, v161, s[38:39]
	v_addc_co_u32_e64 v162, s[40:41], 0, v162, s[40:41]
	v_addc_co_u32_e64 v163, s[42:43], 0, v163, s[42:43]
	v_addc_co_u32_e64 v160, s[44:45], 0, v160, s[44:45]
	v_addc_co_u32_e64 v161, s[46:47], 0, v161, s[46:47]
	v_addc_co_u32_e64 v162, s[48:49], 0, v162, s[48:49]
	v_addc_co_u32_e64 v163, s[50:51], 0, v163, s[50:51]
	s_and_b64 vcc, exec, s[12:13]
	s_cbranch_vccnz .Lsel_red
	v_cmp_le_u32_e64 s[28:29], s35, v77
	v_cmp_le_u32_e64 s[38:39], s35, v71
	v_cmp_le_u32_e64 s[40:41], s35, v91
	v_cmp_le_u32_e64 s[42:43], s35, v85
	v_cmp_le_u32_e64 s[44:45], s35, v105
	v_cmp_le_u32_e64 s[46:47], s35, v99
	v_cmp_le_u32_e64 s[48:49], s35, v116
	v_cmp_le_u32_e64 s[50:51], s35, v60
	v_addc_co_u32_e64 v160, s[28:29], 0, v160, s[28:29]
	v_addc_co_u32_e64 v161, s[38:39], 0, v161, s[38:39]
	v_addc_co_u32_e64 v162, s[40:41], 0, v162, s[40:41]
	v_addc_co_u32_e64 v163, s[42:43], 0, v163, s[42:43]
	v_addc_co_u32_e64 v160, s[44:45], 0, v160, s[44:45]
	v_addc_co_u32_e64 v161, s[46:47], 0, v161, s[46:47]
	v_addc_co_u32_e64 v162, s[48:49], 0, v162, s[48:49]
	v_addc_co_u32_e64 v163, s[50:51], 0, v163, s[50:51]
	s_and_b64 vcc, exec, s[10:11]
	s_cbranch_vccnz .Lsel_red
	v_cmp_le_u32_e64 s[28:29], s35, v78
	v_cmp_le_u32_e64 s[38:39], s35, v72
	v_cmp_le_u32_e64 s[40:41], s35, v92
	v_cmp_le_u32_e64 s[42:43], s35, v86
	v_cmp_le_u32_e64 s[44:45], s35, v106
	v_cmp_le_u32_e64 s[46:47], s35, v100
	v_cmp_le_u32_e64 s[48:49], s35, v117
	v_cmp_le_u32_e64 s[50:51], s35, v112
	v_addc_co_u32_e64 v160, s[28:29], 0, v160, s[28:29]
	v_addc_co_u32_e64 v161, s[38:39], 0, v161, s[38:39]
	v_addc_co_u32_e64 v162, s[40:41], 0, v162, s[40:41]
	v_addc_co_u32_e64 v163, s[42:43], 0, v163, s[42:43]
	v_addc_co_u32_e64 v160, s[44:45], 0, v160, s[44:45]
	v_addc_co_u32_e64 v161, s[46:47], 0, v161, s[46:47]
	v_addc_co_u32_e64 v162, s[48:49], 0, v162, s[48:49]
	v_addc_co_u32_e64 v163, s[50:51], 0, v163, s[50:51]
	s_andn2_b64 vcc, exec, s[82:83]
	s_cbranch_vccnz .Lsel_red
	v_cmp_le_u32_e64 s[28:29], s35, v125
	s_nop 1
	v_addc_co_u32_e64 v160, s[28:29], 0, v160, s[28:29]
.Lsel_red:
	v_add3_u32 v160, v160, v161, v162
	v_add_u32_e32 v160, v160, v163
	s_nop 1
	v_add_u32_dpp v160, v160, v160 quad_perm:[1,0,3,2] row_mask:0xf bank_mask:0xf
	s_nop 1
	v_add_u32_dpp v160, v160, v160 quad_perm:[2,3,0,1] row_mask:0xf bank_mask:0xf
	s_nop 1
	v_add_u32_dpp v160, v160, v160 row_ror:4 row_mask:0xf bank_mask:0xf
	s_nop 1
	v_add_u32_dpp v160, v160, v160 row_ror:8 row_mask:0xf bank_mask:0xf
	s_nop 1
	v_readlane_b32 s28, v160, 0
	v_readlane_b32 s29, v160, 16
	v_readlane_b32 s37, v160, 32
	v_readlane_b32 s38, v160, 48
	s_add_i32 s28, s28, s29
	s_add_i32 s37, s37, s38
	s_add_i32 s36, s28, s37

.LBB0_1253:
	s_cmpk_eq_i32 s36, 0x100
	s_movk_i32 s30, 0x100
	s_cbranch_scc1 .LBB0_1264
	s_mov_b32 s30, s36
	s_branch .LBB0_1265
.LBB0_1263:
	s_mov_b32 s31, s35
	s_mov_b32 s34, s36
	s_xor_b64 s[26:27], s[26:27], -1
	s_xor_b64 s[28:29], s[28:29], -1
	s_andn2_b64 vcc, exec, s[28:29]
	s_cbranch_vccnz .LBB0_1240
	s_branch .LBB0_1266

.LBB0_1483:
	s_or_b64 exec, exec, s[0:1]
	s_waitcnt vmcnt(0)
	v_mov_b32_e32 v7, v228
	s_barrier
	v_mov_b32_e32 v1, 0
	v_readfirstlane_b32 s6, v7
	s_ashr_i32 s12, s6, 6
	s_add_u32 s0, s90, 0x23ab67fc
	s_addc_u32 s1, s91, 0
	v_writelane_b32 v250, s0, 11
	s_lshl_b32 s14, s12, 5
	v_and_b32_e32 v135, 31, v7
	v_writelane_b32 v250, s1, 12
	s_add_u32 s0, s90, 0x19a00800
	s_addc_u32 s1, s91, 0
	v_writelane_b32 v250, s0, 13
	v_ashrrev_i32_e32 v2, 3, v7
	v_bfe_u32 v8, v7, 5, 1
	v_writelane_b32 v250, s1, 14
	s_and_b32 s0, s14, 0xffffffc0
	v_writelane_b32 v250, s0, 15
	s_add_u32 s0, s90, 0x1da40800
	v_writelane_b32 v250, s0, 16
	s_addc_u32 s0, s91, 0
	v_writelane_b32 v250, s0, 17
	s_add_u32 s0, s90, 0x1ea40800
	v_writelane_b32 v250, s0, 18
	s_addc_u32 s0, s91, 0
	v_writelane_b32 v250, s0, 19
	s_movk_i32 s0, 0x90
	v_mul_lo_u32 v9, v2, s0
	v_mad_u32_u24 v160, v135, s0, 0
	s_add_u32 s0, s90, 0x98c0800
	s_addc_u32 s1, s91, 0
	s_add_u32 s8, s90, 0xd900800
	v_writelane_b32 v250, s8, 20
	s_addc_u32 s8, s91, 0
	v_writelane_b32 v250, s8, 21
	s_add_u32 s8, s90, 0x11900800
	v_writelane_b32 v250, s8, 22
	s_addc_u32 s8, s91, 0
	v_writelane_b32 v250, s8, 23
	s_add_u32 s8, s90, 0x237b1800
	v_writelane_b32 v250, s8, 24
	s_addc_u32 s8, s91, 0
	v_writelane_b32 v250, s8, 25
	s_add_u32 s8, s90, 0x23ab5800
	v_writelane_b32 v250, s8, 26
	s_addc_u32 s8, s91, 0
	v_writelane_b32 v250, s8, 27
	s_add_u32 s8, s90, 0x239b1800
	v_lshlrev_b32_e32 v136, 2, v8
	v_writelane_b32 v250, s8, 28
	s_addc_u32 s8, s91, 0
	v_ashrrev_i32_e32 v3, 31, v2
	v_writelane_b32 v250, s8, 29
	v_cmp_gt_u32_e64 s[8:9], v136, v135
	v_lshlrev_b64 v[4:5], 7, v[2:3]
	v_mul_lo_u32 v11, v2, 48
	v_lshlrev_b64 v[140:141], 9, v[2:3]
	v_writelane_b32 v251, s8, 46
	v_or_b32_e32 v2, 2, v136
	v_cmp_gt_u32_e64 s[16:17], v2, v135
	v_writelane_b32 v251, s9, 47
	v_or_b32_e32 v2, 3, v136
	v_writelane_b32 v251, s16, 48
	v_and_b32_e32 v6, 7, v7
	v_lshlrev_b32_e32 v10, 4, v6
	v_writelane_b32 v251, s17, 49
	v_cmp_gt_u32_e64 s[16:17], v2, v135
	v_or_b32_e32 v2, 8, v136
	v_add3_u32 v137, v9, v10, 0
	v_writelane_b32 v251, s16, 54
	v_lshrrev_b32_e32 v9, 2, v7
	v_and_b32_e32 v134, 63, v7
	v_writelane_b32 v251, s17, 55
	v_cmp_gt_u32_e64 s[16:17], v2, v135
	v_or_b32_e32 v2, 9, v136
	v_cmp_eq_u32_e64 s[2:3], 0, v7
	v_writelane_b32 v251, s16, 57
	v_cmp_lt_i32_e64 s[4:5], 63, v7
	v_lshlrev_b32_e32 v139, 2, v7
	v_writelane_b32 v251, s17, 58
	v_cmp_gt_u32_e64 s[16:17], v2, v135
	v_or_b32_e32 v2, 10, v136
	v_and_or_b32 v9, v9, 3, v136
	v_writelane_b32 v251, s16, 59
	v_and_b32_e32 v7, 16, v7
	s_cmp_lt_u32 s6, 64
	v_writelane_b32 v251, s17, 60
	v_cmp_gt_u32_e64 s[16:17], v2, v135
	v_or_b32_e32 v2, 11, v136
	v_mul_u32_u24_e32 v9, 0xc0, v9
	v_writelane_b32 v251, s16, 52
	v_and_or_b32 v7, v139, 12, v7
	s_cselect_b64 s[10:11], -1, 0
	v_writelane_b32 v251, s17, 53
	v_cmp_gt_u32_e64 s[16:17], v2, v135
	v_or_b32_e32 v2, 16, v136
	s_and_b32 s6, s6, 0xc0
	v_writelane_b32 v251, s16, 61
	v_lshlrev_b32_e32 v0, 3, v6
	v_lshlrev_b32_e32 v6, 3, v8
	v_writelane_b32 v251, s17, 62
	v_cmp_gt_u32_e64 s[16:17], v2, v135
	v_or_b32_e32 v2, 17, v136
	v_lshl_or_b32 v7, v7, 1, v9
	v_writelane_b32 v250, s16, 7
	v_lshlrev_b32_e32 v161, 4, v8
	s_cmp_lt_i32 s12, 4
	v_writelane_b32 v250, s17, 8
	v_cmp_gt_u32_e64 s[16:17], v2, v135
	v_or_b32_e32 v2, 18, v136
	v_cmp_gt_u32_e64 s[26:27], v2, v135
	v_or_b32_e32 v2, 19, v136
	v_cmp_gt_u32_e64 s[28:29], v2, v135
	v_or_b32_e32 v2, 24, v136
	v_cmp_gt_u32_e64 s[30:31], v2, v135
	v_or_b32_e32 v2, 25, v136
	v_writelane_b32 v250, s16, 9
	v_cmp_gt_u32_e64 s[34:35], v2, v135
	v_or_b32_e32 v2, 26, v136
	v_writelane_b32 v250, s17, 10
	v_cmp_gt_u32_e64 s[36:37], v2, v135
	v_or_b32_e32 v2, 27, v136
	s_mov_b32 s7, 0
	v_add_u32_e32 v162, 0, v7
	v_lshlrev_b32_e32 v138, 6, v134
	v_add_u32_e32 v163, 0, v161
	v_or_b32_e32 v142, 0x10000, v135
	v_cmp_lt_u32_e64 s[8:9], v136, v135
	v_cmp_gt_u32_e64 s[38:39], v2, v135
	v_mov_b32_e32 v143, v1
	v_writelane_b32 v250, s6, 30
	s_cselect_b64 s[12:13], -1, 0
	v_and_or_b32 v164, s14, 32, v135
	v_or_b32_e32 v165, 0xf40, v136
	v_or_b32_e32 v166, 0xf80, v136
	v_lshlrev_b64 v[144:145], 1, v[4:5]
	v_add_u32_e32 v167, v137, v11
	s_mov_b32 s16, 0x41000000
	v_mov_b32_e32 v168, 0x260
	v_mov_b32_e32 v169, 0x41c00000
	s_mov_b32 s17, 0xc1c00000
	v_mov_b32_e32 v170, 0x23ab5000
	v_mov_b32_e32 v171, 0x4000
	v_lshlrev_b32_e32 v146, 1, v0
	v_lshlrev_b32_e32 v148, 1, v6
	v_mov_b32_e32 v172, 0xff800000
	v_writelane_b32 v250, s14, 31
	s_and_saveexec_b64 s[14:15], s[2:3]
	s_cbranch_execz .Lq3_pre
	v_readlane_b32 s18, v250, 11
	v_readlane_b32 s19, v250, 12
	v_mov_b32_e32 v2, 1
	s_nop 3
	global_atomic_add v255, v1, v2, s[18:19] sc0
.Lq3_pre:
	s_or_b64 exec, exec, s[14:15]
	s_branch .LBB0_1486

.LBB0_1486:
	s_and_saveexec_b64 s[14:15], s[2:3]
	s_cbranch_execz .LBB0_1490
	v_readlane_b32 s18, v250, 11
	v_readlane_b32 s19, v250, 12
	s_waitcnt vmcnt(0)
	ds_write_b32 v1, v255 offset:60000
	v_mov_b32_e32 v2, 1
	s_nop 1
	global_atomic_add v255, v1, v2, s[18:19] sc0
